# P1: each unit's first 16 LDS fragment reads issued at the top of the unit header (addresses are phase constants) so their latency overlaps the scalar tile-map code
# baseline (speedup 1.0000x reference)
; #define PG8_STAGE(bufoff, gbase, voff) do { _Pragma("unroll") for (int _i = 0; _i < 2; ++_i) \
;         __builtin_amdgcn_global_load_lds((const unsigned*)((const char*)(gbase) + (voff)[_i]), (PG8_LAS unsigned*)(lds + (bufoff) + ldsw + _i * 8192), 16, 0, 0); } while (0)
; #define PG8_LDA(dst, b, h) do { _Pragma("unroll") for (int m = 0; m < 4; ++m) _Pragma("unroll") for (int k = 0; k < 2; ++k) dst[m][k] = *(const PG8_LAS bf16x8*)(lds + PG8_SA(b, h) + aoff + m * 2048 + k * 1024); } while (0)
; #define PG8_LDB(dst, b, h) do { _Pragma("unroll") for (int n = 0; n < 2; ++n) _Pragma("unroll") for (int k = 0; k < 2; ++k) dst[n][k] = *(const PG8_LAS bf16x8*)(lds + PG8_SB(b, h) + boff + n * 2048 + k * 1024); } while (0)
; #define PG8_SCHED __builtin_amdgcn_sched_barrier(0)
;     __host__ __device__ bool next(int i, Unit& u) const {
;         const long L = (long)i * G + c; if (L >= nwg) return false;
;         int wgid = (int)L; { const int q = nwg / NXCD, r = nwg % NXCD, xcd = wgid % NXCD, off = wgid / NXCD; wgid = (xcd < r ? xcd * (q + 1) : r * (q + 1) + (xcd - r) * q) + off; }
;         const int nig = WGM * nN, gid = wgid / nig, fm = gid * WGM, gsz = (nM - fm) < WGM ? (nM - fm) : WGM;
;         u.pm = fm + ((wgid % nig) % gsz); u.pn = (wgid % nig) / gsz + ((gid & 1) ? rot : 0); if (u.pn >= nN) u.pn -= nN; return true;
; template <class Epi, class Sched, bool ALIGN_EPI = false, bool SP2 = false>
; __device__ __forceinline__ void gemm_phase(PG8_LAS unsigned char* lds, const Gemm g, const Sched& S, const Epi& E) {
;     ...
;             PG8_LDB(B0, 0, 0); PG8_LDB(B1, 0, 1); PG8_SCHED; PG8_LDA(At, 0, 0); PG8_STAGE(PG8_SA(1, 1), a1 + hstep, voffA);
.LBB0_140:
	ds_read_b128 v[130:133], v193
	ds_read_b128 v[134:137], v193 offset:1024
	ds_read_b128 v[138:141], v193 offset:2048
	ds_read_b128 v[142:145], v193 offset:3072
	ds_read_b128 v[166:169], v194
	ds_read_b128 v[170:173], v194 offset:1024
	ds_read_b128 v[174:177], v194 offset:2048
	ds_read_b128 v[178:181], v194 offset:3072
	ds_read_b128 v[182:185], v195
	ds_read_b128 v[186:189], v195 offset:1024
	ds_read_b128 v[200:203], v195 offset:2048
	ds_read_b128 v[204:207], v195 offset:3072
	ds_read_b128 v[208:211], v195 offset:4096
	ds_read_b128 v[212:215], v195 offset:5120
	ds_read_b128 v[216:219], v195 offset:6144
	ds_read_b128 v[220:223], v195 offset:7168
	s_add_i32 s0, s0, 1
	s_mul_i32 s1, s0, s33
	s_mul_hi_u32 s8, s0, s3
	s_add_i32 s8, s8, s1
	s_mul_i32 s1, s0, s3
	s_add_u32 s84, s1, s96
	s_addc_u32 s85, s8, s6
	v_cmp_gt_i64_e32 vcc, s[84:85], v[164:165]
	v_cmp_lt_i64_e64 s[8:9], s[84:85], v[160:161]
	s_cbranch_vccnz .LBB0_142
	s_ashr_i32 s1, s84, 31
	s_lshr_b32 s1, s1, 29
	s_add_i32 s1, s84, s1
	s_ashr_i32 s11, s1, 3
	s_and_b32 s1, s1, -8
	s_sub_i32 s1, s84, s1
	s_cmp_lt_i32 s1, 0
	s_movk_i32 s79, 0x181
	s_cselect_b32 s79, s79, 0x180
	s_mul_i32 s1, s1, s79
	s_add_i32 s1, s1, s11
	s_mul_hi_i32 s11, s1, 0x2aaaaaab
	s_lshr_b32 s79, s11, 31
	s_ashr_i32 s11, s11, 5
	s_add_i32 s11, s11, s79
	s_lshl_b32 s79, s11, 3
	s_sub_i32 s80, 0x80, s79
	s_min_i32 s80, s80, 8
	s_mul_i32 s82, s11, 0xc0
	s_sub_i32 s1, s1, s82
	s_ashr_i32 s81, s1, 3
	s_mul_i32 s80, s81, s80
	s_sub_i32 s1, s1, s80
	s_add_i32 s80, s79, s1
	s_lshl_b32 s1, s11, 1
	s_and_b32 s1, s1, 2
	s_add_i32 s1, s1, s81
	s_cmp_lt_i32 s1, 24
	s_cselect_b32 s11, 0, 0xffffffe8
	s_add_i32 s82, s11, s1
.LBB0_142:
	s_ashr_i32 s81, s80, 31
	s_lshl_b64 s[84:85], s[80:81], 19
	s_add_u32 s84, s98, s84
	s_addc_u32 s85, s99, s85
	s_and_b64 s[86:87], s[8:9], exec
	s_cselect_b32 s1, s85, s89
	s_cselect_b32 s11, s84, s88
	s_ashr_i32 s83, s82, 31
	s_lshl_b64 s[86:87], s[82:83], 19
	s_add_u32 s86, s4, s86
	s_addc_u32 s87, s5, s87
	s_and_b64 s[92:93], s[8:9], exec
	s_cselect_b32 s79, s87, s91
	s_cselect_b32 s81, s86, s90
	s_add_u32 s88, s88, 0x40080
	s_addc_u32 s89, s89, 0
	s_add_u32 s83, s90, 0x100
	s_addc_u32 vcc_lo, s91, 0
	s_mov_b32 vcc_hi, -2
	s_add_u32 s90, s88, 0xfffc0080
	s_addc_u32 s91, s89, -1
	s_cmp_eq_u32 vcc_hi, 12
	s_cselect_b32 s93, s1, s91
	s_cselect_b32 s92, s11, s90
	s_cselect_b32 s91, s79, vcc_lo
	s_cselect_b32 s90, s81, s83
	v_lshl_add_u64 v[190:191], s[88:89], 0, v[156:157]
	s_add_i32 m0, s58, 0xc000
	global_load_lds_dwordx4 v[190:191], off
	v_lshl_add_u64 v[190:191], s[88:89], 0, v[158:159]
	s_add_i32 m0, s58, 0xe000
	s_nop 0
	global_load_lds_dwordx4 v[190:191], off
	s_waitcnt vmcnt(8)
	s_waitcnt lgkmcnt(0)
	s_barrier
	s_setprio 1
	s_waitcnt lgkmcnt(0)
	v_mfma_f32_16x16x32_bf16 v[126:129], v[130:133], v[182:185], 0
	v_mfma_f32_16x16x32_bf16 v[122:125], v[138:141], v[182:185], 0
	v_mfma_f32_16x16x32_bf16 v[110:113], v[130:133], v[200:203], 0
	v_mfma_f32_16x16x32_bf16 v[106:109], v[138:141], v[200:203], 0
	v_mfma_f32_16x16x32_bf16 v[94:97], v[130:133], v[208:211], 0
	v_mfma_f32_16x16x32_bf16 v[90:93], v[138:141], v[208:211], 0
	v_mfma_f32_16x16x32_bf16 v[78:81], v[130:133], v[216:219], 0
	v_mfma_f32_16x16x32_bf16 v[74:77], v[138:141], v[216:219], 0
	v_mfma_f32_16x16x32_bf16 v[126:129], v[134:137], v[186:189], v[126:129]
	v_mfma_f32_16x16x32_bf16 v[122:125], v[142:145], v[186:189], v[122:125]
	v_mfma_f32_16x16x32_bf16 v[110:113], v[134:137], v[204:207], v[110:113]
	v_mfma_f32_16x16x32_bf16 v[106:109], v[142:145], v[204:207], v[106:109]
	v_mfma_f32_16x16x32_bf16 v[94:97], v[134:137], v[212:215], v[94:97]
	v_mfma_f32_16x16x32_bf16 v[90:93], v[142:145], v[212:215], v[90:93]
	v_mfma_f32_16x16x32_bf16 v[78:81], v[134:137], v[220:223], v[78:81]
	v_mfma_f32_16x16x32_bf16 v[74:77], v[142:145], v[220:223], v[74:77]
	v_mfma_f32_16x16x32_bf16 v[118:121], v[166:169], v[182:185], 0
	v_mfma_f32_16x16x32_bf16 v[114:117], v[174:177], v[182:185], 0
	v_mfma_f32_16x16x32_bf16 v[102:105], v[166:169], v[200:203], 0
	v_mfma_f32_16x16x32_bf16 v[98:101], v[174:177], v[200:203], 0
	v_mfma_f32_16x16x32_bf16 v[86:89], v[166:169], v[208:211], 0
	v_mfma_f32_16x16x32_bf16 v[82:85], v[174:177], v[208:211], 0
	v_mfma_f32_16x16x32_bf16 v[70:73], v[166:169], v[216:219], 0
	v_mfma_f32_16x16x32_bf16 v[66:69], v[174:177], v[216:219], 0
	v_mfma_f32_16x16x32_bf16 v[118:121], v[170:173], v[186:189], v[118:121]
	v_mfma_f32_16x16x32_bf16 v[114:117], v[178:181], v[186:189], v[114:117]
	v_mfma_f32_16x16x32_bf16 v[102:105], v[170:173], v[204:207], v[102:105]
	v_mfma_f32_16x16x32_bf16 v[98:101], v[178:181], v[204:207], v[98:101]
	v_mfma_f32_16x16x32_bf16 v[86:89], v[170:173], v[212:215], v[86:89]
	v_mfma_f32_16x16x32_bf16 v[82:85], v[178:181], v[212:215], v[82:85]
	v_mfma_f32_16x16x32_bf16 v[70:73], v[170:173], v[220:223], v[70:73]
	v_mfma_f32_16x16x32_bf16 v[66:69], v[178:181], v[220:223], v[66:69]
	s_setprio 0
	s_barrier
	s_add_i32 s94, s7, s97
	v_lshl_add_u64 v[190:191], s[90:91], 0, v[148:149]
	s_mov_b32 m0, s94
	ds_read_b128 v[182:185], v195 offset:16384
	ds_read_b128 v[186:189], v195 offset:17408
	ds_read_b128 v[200:203], v195 offset:18432
	ds_read_b128 v[204:207], v195 offset:19456
	ds_read_b128 v[208:211], v195 offset:20480
	ds_read_b128 v[212:215], v195 offset:21504
	ds_read_b128 v[216:219], v195 offset:22528
	ds_read_b128 v[220:223], v195 offset:23552
	global_load_lds_dwordx4 v[190:191], off
	s_add_i32 m0, s94, 0x2000
	s_add_u32 s94, s90, 0x40000
	v_lshl_add_u64 v[224:225], s[90:91], 0, v[152:153]
	s_addc_u32 s95, s91, 0
	s_add_i32 s18, s64, s97
	global_load_lds_dwordx4 v[224:225], off
	v_lshl_add_u64 v[226:227], s[94:95], 0, v[148:149]
	s_mov_b32 m0, s18
	v_lshl_add_u64 v[228:229], s[92:93], 0, v[150:151]
	global_load_lds_dwordx4 v[226:227], off
	v_lshl_add_u64 v[226:227], s[94:95], 0, v[152:153]
	s_add_i32 m0, s18, 0x2000
	s_nop 0
	global_load_lds_dwordx4 v[226:227], off
	v_lshl_add_u64 v[226:227], s[92:93], 0, v[146:147]
	s_mov_b32 m0, s58
	s_nop 0
	global_load_lds_dwordx4 v[226:227], off
	s_mov_b32 m0, s59
	s_nop 0
	global_load_lds_dwordx4 v[228:229], off
	s_waitcnt vmcnt(8)
	s_waitcnt lgkmcnt(0)
	s_barrier
; #define PG8_STAGE(bufoff, gbase, voff) do { _Pragma("unroll") for (int _i = 0; _i < 2; ++_i) \
;         __builtin_amdgcn_global_load_lds((const unsigned*)((const char*)(gbase) + (voff)[_i]), (PG8_LAS unsigned*)(lds + (bufoff) + ldsw + _i * 8192), 16, 0, 0); } while (0)
; #define PG8_LDA(dst, b, h) do { _Pragma("unroll") for (int m = 0; m < 4; ++m) _Pragma("unroll") for (int k = 0; k < 2; ++k) dst[m][k] = *(const PG8_LAS bf16x8*)(lds + PG8_SA(b, h) + aoff + m * 2048 + k * 1024); } while (0)
; #define PG8_LDB(dst, b, h) do { _Pragma("unroll") for (int n = 0; n < 2; ++n) _Pragma("unroll") for (int k = 0; k < 2; ++k) dst[n][k] = *(const PG8_LAS bf16x8*)(lds + PG8_SB(b, h) + boff + n * 2048 + k * 1024); } while (0)
; #define PG8_MMA(ai, bj, At, Bt) do { __builtin_amdgcn_s_setprio(1); _Pragma("unroll") for (int m = 0; m < 4; ++m) _Pragma("unroll") for (int n = 0; n < 2; ++n) _Pragma("unroll") for (int k = 0; k < 2; ++k) \
;         acc[ai][bj][m][n] = __builtin_amdgcn_mfma_f32_16x16x32_bf16(Bt[n][k], At[m][k], acc[ai][bj][m][n], 0, 0, 0); __builtin_amdgcn_s_setprio(0); } while (0)
; #define PG8_WAIT_V(n) asm volatile("s_waitcnt vmcnt(" #n ")" ::: "memory")
; #define PG8_WAIT_L(n) asm volatile("s_waitcnt lgkmcnt(" #n ")" ::: "memory")
; #define PG8_BAR __builtin_amdgcn_s_barrier()
; #define PG8_SCHED __builtin_amdgcn_sched_barrier(0)
; template <class Epi, class Sched, bool ALIGN_EPI = false, bool SP2 = false>
; __device__ __forceinline__ void gemm_phase(PG8_LAS unsigned char* lds, const Gemm g, const Sched& S, const Epi& E) {
;     ...
;             PG8_LDA(At, 0, 1); PG8_STAGE(PG8_SB(0, 0), b2, voffB); PG8_STAGE(PG8_SB(0, 1), b2 + hstep, voffB); PG8_STAGE(PG8_SA(0, 0), a2, voffA);
;             PG8_WAIT_V(8); PG8_WAIT_L(0); PG8_BAR; PG8_MMA(1, 0, At, B0); PG8_MMA(1, 1, At, B1); PG8_BAR; PG8_SCHED;
;             PG8_LDB(B0, 1, 0); PG8_LDB(B1, 1, 1); PG8_SCHED; PG8_LDA(At, 1, 0); PG8_STAGE(PG8_SA(0, 1), a2 + hstep, voffA);
;             PG8_WAIT_V(8); PG8_WAIT_L(0); PG8_BAR; PG8_MMA(0, 0, At, B0); PG8_MMA(0, 1, At, B1); PG8_BAR; PG8_SCHED;
	s_setprio 1
	s_waitcnt lgkmcnt(0)
	v_mfma_f32_16x16x32_bf16 v[62:65], v[130:133], v[182:185], 0
	v_mfma_f32_16x16x32_bf16 v[58:61], v[138:141], v[182:185], 0
	v_mfma_f32_16x16x32_bf16 v[46:49], v[130:133], v[200:203], 0
	v_mfma_f32_16x16x32_bf16 v[42:45], v[138:141], v[200:203], 0
	v_mfma_f32_16x16x32_bf16 v[30:33], v[130:133], v[208:211], 0
	v_mfma_f32_16x16x32_bf16 v[26:29], v[138:141], v[208:211], 0
	v_mfma_f32_16x16x32_bf16 v[14:17], v[130:133], v[216:219], 0
	v_mfma_f32_16x16x32_bf16 v[10:13], v[138:141], v[216:219], 0
	v_mfma_f32_16x16x32_bf16 v[62:65], v[134:137], v[186:189], v[62:65]
	v_mfma_f32_16x16x32_bf16 v[58:61], v[142:145], v[186:189], v[58:61]
	v_mfma_f32_16x16x32_bf16 v[46:49], v[134:137], v[204:207], v[46:49]
	v_mfma_f32_16x16x32_bf16 v[42:45], v[142:145], v[204:207], v[42:45]
	v_mfma_f32_16x16x32_bf16 v[30:33], v[134:137], v[212:215], v[30:33]
	v_mfma_f32_16x16x32_bf16 v[26:29], v[142:145], v[212:215], v[26:29]
	v_mfma_f32_16x16x32_bf16 v[14:17], v[134:137], v[220:223], v[14:17]
	v_mfma_f32_16x16x32_bf16 v[10:13], v[142:145], v[220:223], v[10:13]
	v_mfma_f32_16x16x32_bf16 v[54:57], v[166:169], v[182:185], 0
	v_mfma_f32_16x16x32_bf16 v[50:53], v[174:177], v[182:185], 0
	v_mfma_f32_16x16x32_bf16 v[38:41], v[166:169], v[200:203], 0
	v_mfma_f32_16x16x32_bf16 v[34:37], v[174:177], v[200:203], 0
	v_mfma_f32_16x16x32_bf16 v[22:25], v[166:169], v[208:211], 0
	v_mfma_f32_16x16x32_bf16 v[18:21], v[174:177], v[208:211], 0
	v_mfma_f32_16x16x32_bf16 v[6:9], v[166:169], v[216:219], 0
	v_mfma_f32_16x16x32_bf16 v[2:5], v[174:177], v[216:219], 0
	v_mfma_f32_16x16x32_bf16 v[54:57], v[170:173], v[186:189], v[54:57]
	v_mfma_f32_16x16x32_bf16 v[50:53], v[178:181], v[186:189], v[50:53]
	v_mfma_f32_16x16x32_bf16 v[38:41], v[170:173], v[204:207], v[38:41]
	v_mfma_f32_16x16x32_bf16 v[34:37], v[178:181], v[204:207], v[34:37]
	v_mfma_f32_16x16x32_bf16 v[22:25], v[170:173], v[212:215], v[22:25]
	v_mfma_f32_16x16x32_bf16 v[18:21], v[178:181], v[212:215], v[18:21]
	v_mfma_f32_16x16x32_bf16 v[6:9], v[170:173], v[220:223], v[6:9]
	v_mfma_f32_16x16x32_bf16 v[2:5], v[178:181], v[220:223], v[2:5]
	s_setprio 0
	s_barrier
	s_add_i32 s18, 0, 0x18000
	s_add_i32 s94, 0, 0x1c000
	v_add_u32_e32 v142, s18, v192
	v_add_u32_e32 v154, s94, v192
	ds_read_b128 v[130:133], v142
	ds_read_b128 v[134:137], v142 offset:1024
	ds_read_b128 v[138:141], v142 offset:2048
	ds_read_b128 v[142:145], v142 offset:3072
	ds_read_b128 v[166:169], v154
	ds_read_b128 v[170:173], v154 offset:1024
	ds_read_b128 v[174:177], v154 offset:2048
	ds_read_b128 v[178:181], v154 offset:3072
	s_add_u32 s92, s92, 0x40000
	s_addc_u32 s93, s93, 0
	s_mov_b32 m0, s56
	v_lshl_add_u64 v[230:231], s[92:93], 0, v[146:147]
	ds_read_b128 v[182:185], v195 offset:32768
	ds_read_b128 v[186:189], v195 offset:33792
	ds_read_b128 v[200:203], v195 offset:34816
	ds_read_b128 v[204:207], v195 offset:35840
	ds_read_b128 v[208:211], v195 offset:36864
	ds_read_b128 v[212:215], v195 offset:37888
	ds_read_b128 v[216:219], v195 offset:38912
	ds_read_b128 v[220:223], v195 offset:39936
	global_load_lds_dwordx4 v[230:231], off
	v_lshl_add_u64 v[230:231], s[92:93], 0, v[150:151]
	s_mov_b32 m0, s57
	s_nop 0
	global_load_lds_dwordx4 v[230:231], off
	s_waitcnt vmcnt(8)
	s_waitcnt lgkmcnt(0)
	s_barrier
	s_setprio 1
	s_waitcnt lgkmcnt(0)
	v_mfma_f32_16x16x32_bf16 v[126:129], v[130:133], v[182:185], v[126:129]
	v_mfma_f32_16x16x32_bf16 v[122:125], v[138:141], v[182:185], v[122:125]
	v_mfma_f32_16x16x32_bf16 v[110:113], v[130:133], v[200:203], v[110:113]
	v_mfma_f32_16x16x32_bf16 v[106:109], v[138:141], v[200:203], v[106:109]
	v_mfma_f32_16x16x32_bf16 v[94:97], v[130:133], v[208:211], v[94:97]
	v_mfma_f32_16x16x32_bf16 v[90:93], v[138:141], v[208:211], v[90:93]
	v_mfma_f32_16x16x32_bf16 v[78:81], v[130:133], v[216:219], v[78:81]
	v_mfma_f32_16x16x32_bf16 v[74:77], v[138:141], v[216:219], v[74:77]
	v_mfma_f32_16x16x32_bf16 v[126:129], v[134:137], v[186:189], v[126:129]
	v_mfma_f32_16x16x32_bf16 v[122:125], v[142:145], v[186:189], v[122:125]
	v_mfma_f32_16x16x32_bf16 v[110:113], v[134:137], v[204:207], v[110:113]
	v_mfma_f32_16x16x32_bf16 v[106:109], v[142:145], v[204:207], v[106:109]
	v_mfma_f32_16x16x32_bf16 v[94:97], v[134:137], v[212:215], v[94:97]
	v_mfma_f32_16x16x32_bf16 v[90:93], v[142:145], v[212:215], v[90:93]
	v_mfma_f32_16x16x32_bf16 v[78:81], v[134:137], v[220:223], v[78:81]
	v_mfma_f32_16x16x32_bf16 v[74:77], v[142:145], v[220:223], v[74:77]
	v_mfma_f32_16x16x32_bf16 v[118:121], v[166:169], v[182:185], v[118:121]
	v_mfma_f32_16x16x32_bf16 v[114:117], v[174:177], v[182:185], v[114:117]
	v_mfma_f32_16x16x32_bf16 v[102:105], v[166:169], v[200:203], v[102:105]
	v_mfma_f32_16x16x32_bf16 v[98:101], v[174:177], v[200:203], v[98:101]
	v_mfma_f32_16x16x32_bf16 v[86:89], v[166:169], v[208:211], v[86:89]
	v_mfma_f32_16x16x32_bf16 v[82:85], v[174:177], v[208:211], v[82:85]
	v_mfma_f32_16x16x32_bf16 v[70:73], v[166:169], v[216:219], v[70:73]
	v_mfma_f32_16x16x32_bf16 v[66:69], v[174:177], v[216:219], v[66:69]
	v_mfma_f32_16x16x32_bf16 v[118:121], v[170:173], v[186:189], v[118:121]
	v_mfma_f32_16x16x32_bf16 v[114:117], v[178:181], v[186:189], v[114:117]
	v_mfma_f32_16x16x32_bf16 v[102:105], v[170:173], v[204:207], v[102:105]
	v_mfma_f32_16x16x32_bf16 v[98:101], v[178:181], v[204:207], v[98:101]
	v_mfma_f32_16x16x32_bf16 v[86:89], v[170:173], v[212:215], v[86:89]
	v_mfma_f32_16x16x32_bf16 v[82:85], v[178:181], v[212:215], v[82:85]
	v_mfma_f32_16x16x32_bf16 v[70:73], v[170:173], v[220:223], v[70:73]
	v_mfma_f32_16x16x32_bf16 v[66:69], v[178:181], v[220:223], v[66:69]
	s_setprio 0
	s_barrier
; #define PG8_STAGE(bufoff, gbase, voff) do { _Pragma("unroll") for (int _i = 0; _i < 2; ++_i) \
;         __builtin_amdgcn_global_load_lds((const unsigned*)((const char*)(gbase) + (voff)[_i]), (PG8_LAS unsigned*)(lds + (bufoff) + ldsw + _i * 8192), 16, 0, 0); } while (0)
; #define PG8_LDA(dst, b, h) do { _Pragma("unroll") for (int m = 0; m < 4; ++m) _Pragma("unroll") for (int k = 0; k < 2; ++k) dst[m][k] = *(const PG8_LAS bf16x8*)(lds + PG8_SA(b, h) + aoff + m * 2048 + k * 1024); } while (0)
; #define PG8_MMA(ai, bj, At, Bt) do { __builtin_amdgcn_s_setprio(1); _Pragma("unroll") for (int m = 0; m < 4; ++m) _Pragma("unroll") for (int n = 0; n < 2; ++n) _Pragma("unroll") for (int k = 0; k < 2; ++k) \
;         acc[ai][bj][m][n] = __builtin_amdgcn_mfma_f32_16x16x32_bf16(Bt[n][k], At[m][k], acc[ai][bj][m][n], 0, 0, 0); __builtin_amdgcn_s_setprio(0); } while (0)
; #define PG8_WAIT_V(n) asm volatile("s_waitcnt vmcnt(" #n ")" ::: "memory")
; #define PG8_WAIT_L(n) asm volatile("s_waitcnt lgkmcnt(" #n ")" ::: "memory")
; #define PG8_BAR __builtin_amdgcn_s_barrier()
; #define PG8_SCHED __builtin_amdgcn_sched_barrier(0)
; template <class Epi, class Sched, bool ALIGN_EPI = false, bool SP2 = false>
; __device__ __forceinline__ void gemm_phase(PG8_LAS unsigned char* lds, const Gemm g, const Sched& S, const Epi& E) {
;     ...
;             PG8_LDA(At, 1, 1); PG8_STAGE(PG8_SB(1, 0), b3, voffB); PG8_STAGE(PG8_SB(1, 1), b3 + hstep, voffB); PG8_STAGE(PG8_SA(1, 0), a3, voffA);
;             PG8_WAIT_V(8); PG8_WAIT_L(0); PG8_BAR; PG8_MMA(1, 0, At, B0); PG8_MMA(1, 1, At, B1); PG8_BAR; PG8_SCHED;
	s_add_i32 s18, s18, s97
	v_lshl_add_u64 v[190:191], v[190:191], 0, s[74:75]
	s_mov_b32 m0, s18
	ds_read_b128 v[182:185], v195 offset:49152
	ds_read_b128 v[186:189], v195 offset:50176
	ds_read_b128 v[200:203], v195 offset:51200
	ds_read_b128 v[204:207], v195 offset:52224
	ds_read_b128 v[208:211], v195 offset:53248
	ds_read_b128 v[212:215], v195 offset:54272
	ds_read_b128 v[216:219], v195 offset:55296
	ds_read_b128 v[220:223], v195 offset:56320
	global_load_lds_dwordx4 v[190:191], off
	s_add_i32 m0, s18, 0x2000
	s_add_u32 s90, s90, 0x40080
	v_lshl_add_u64 v[190:191], v[224:225], 0, s[74:75]
	s_addc_u32 s91, s91, 0
	s_add_i32 s18, s94, s97
	global_load_lds_dwordx4 v[190:191], off
	v_lshl_add_u64 v[190:191], s[90:91], 0, v[148:149]
	s_mov_b32 m0, s18
	s_nop 0
	global_load_lds_dwordx4 v[190:191], off
	v_lshl_add_u64 v[190:191], s[90:91], 0, v[152:153]
	s_add_i32 m0, s18, 0x2000
	s_nop 0
	global_load_lds_dwordx4 v[190:191], off
	v_lshl_add_u64 v[190:191], v[226:227], 0, s[74:75]
	s_mov_b32 m0, s19
	s_nop 0
	global_load_lds_dwordx4 v[190:191], off
	v_lshl_add_u64 v[190:191], v[228:229], 0, s[74:75]
	s_mov_b32 m0, s66
	s_nop 0
	global_load_lds_dwordx4 v[190:191], off
	s_waitcnt vmcnt(8)
	s_waitcnt lgkmcnt(0)
	s_barrier
	s_setprio 1
	s_waitcnt lgkmcnt(0)
	v_mfma_f32_16x16x32_bf16 v[62:65], v[130:133], v[182:185], v[62:65]
	v_mfma_f32_16x16x32_bf16 v[58:61], v[138:141], v[182:185], v[58:61]
	v_mfma_f32_16x16x32_bf16 v[46:49], v[130:133], v[200:203], v[46:49]
	v_mfma_f32_16x16x32_bf16 v[42:45], v[138:141], v[200:203], v[42:45]
	v_mfma_f32_16x16x32_bf16 v[30:33], v[130:133], v[208:211], v[30:33]
	v_mfma_f32_16x16x32_bf16 v[26:29], v[138:141], v[208:211], v[26:29]
	v_mfma_f32_16x16x32_bf16 v[14:17], v[130:133], v[216:219], v[14:17]
	v_mfma_f32_16x16x32_bf16 v[10:13], v[138:141], v[216:219], v[10:13]
	v_mfma_f32_16x16x32_bf16 v[62:65], v[134:137], v[186:189], v[62:65]
	v_mfma_f32_16x16x32_bf16 v[58:61], v[142:145], v[186:189], v[58:61]
	v_mfma_f32_16x16x32_bf16 v[46:49], v[134:137], v[204:207], v[46:49]
	v_mfma_f32_16x16x32_bf16 v[42:45], v[142:145], v[204:207], v[42:45]
	v_mfma_f32_16x16x32_bf16 v[30:33], v[134:137], v[212:215], v[30:33]
	v_mfma_f32_16x16x32_bf16 v[26:29], v[142:145], v[212:215], v[26:29]
	v_mfma_f32_16x16x32_bf16 v[14:17], v[134:137], v[220:223], v[14:17]
	v_mfma_f32_16x16x32_bf16 v[10:13], v[142:145], v[220:223], v[10:13]
	v_mfma_f32_16x16x32_bf16 v[54:57], v[166:169], v[182:185], v[54:57]
	v_mfma_f32_16x16x32_bf16 v[50:53], v[174:177], v[182:185], v[50:53]
	v_mfma_f32_16x16x32_bf16 v[38:41], v[166:169], v[200:203], v[38:41]
	v_mfma_f32_16x16x32_bf16 v[34:37], v[174:177], v[200:203], v[34:37]
	v_mfma_f32_16x16x32_bf16 v[22:25], v[166:169], v[208:211], v[22:25]
	v_mfma_f32_16x16x32_bf16 v[18:21], v[174:177], v[208:211], v[18:21]
	v_mfma_f32_16x16x32_bf16 v[6:9], v[166:169], v[216:219], v[6:9]
	v_mfma_f32_16x16x32_bf16 v[2:5], v[174:177], v[216:219], v[2:5]
	v_mfma_f32_16x16x32_bf16 v[54:57], v[170:173], v[186:189], v[54:57]
	v_mfma_f32_16x16x32_bf16 v[50:53], v[178:181], v[186:189], v[50:53]
	v_mfma_f32_16x16x32_bf16 v[38:41], v[170:173], v[204:207], v[38:41]
	v_mfma_f32_16x16x32_bf16 v[34:37], v[178:181], v[204:207], v[34:37]
	v_mfma_f32_16x16x32_bf16 v[22:25], v[170:173], v[212:215], v[22:25]
	v_mfma_f32_16x16x32_bf16 v[18:21], v[178:181], v[212:215], v[18:21]
	v_mfma_f32_16x16x32_bf16 v[6:9], v[170:173], v[220:223], v[6:9]
	v_mfma_f32_16x16x32_bf16 v[2:5], v[178:181], v[220:223], v[2:5]
	s_setprio 0
	s_barrier
	s_add_i32 vcc_hi, vcc_hi, 2
	s_add_u32 s88, s88, 0x100
	s_addc_u32 s89, s89, 0
	s_add_u32 s83, s83, 0x100
	s_addc_u32 vcc_lo, vcc_lo, 0
	s_cmp_gt_u32 vcc_hi, 13
